# ESMALL forget-gate scan made batch-local (b = XCD), so GIN(even)->ESMALL->EGEMM barriers are XCD-local too (24 of 36 local)
# speedup vs baseline: 1.0180x; 1.0015x over previous
; __device__ __forceinline__ float bf2f(bf16_t v) { return __uint_as_float(((unsigned)v) << 16); }
; __device__ __forceinline__ void phase_even_small(const Frame& F, const Params& p, int li) {
;     ...
;     for (int bh = F.bx; bh < 64; bh += F.G) {
;         const int b = bh >> 3, h = bh & 7;
;         const float bf = p.in[6][li * 8 + h];
;         float v[8]; float carry = 0.f;
; #pragma unroll
;         for (int j = 0; j < 8; ++j) {
;             const int s = 512 * F.wave + 64 * j + lane_l;
;             const float xg = bf2f(proj[((size_t)b * SEQ + s) * EIN_NP + C_FG + h]) + bf;
;             float ls = (xg >= 0.f) ? -log1pf(expf(-xg)) : (xg - log1pf(expf(xg)));
; #pragma unroll
;             for (int d = 1; d < 64; d <<= 1) { const float t_ = __int_as_float(__builtin_amdgcn_ds_bpermute(((lane_l - d) & 63) << 2, __float_as_int(ls))); if (lane_l >= d) ls += t_; }
;             v[j] = ls + carry;
;             carry = __int_as_float(__builtin_amdgcn_readlane(__float_as_int(v[j]), 63));
;         }
;         __syncthreads();
;         if (lane_l == 0) tot[F.wave] = carry;
;         __syncthreads();
;         float off = 0.f;
; #pragma unroll
;         for (int w = 0; w < 8; ++w) { const float tw = tot[w]; if (w < F.wave) off += tw; }
; #pragma unroll
;         for (int j = 0; j < 8; ++j) ccum[(size_t)bh * SEQ + 512 * F.wave + 64 * j + lane_l] = (v[j] + off) * LOG2E;
.LBB0_509:
	s_cmp_gt_i32 s96, 63
	s_cbranch_scc1 .LBB0_562
	v_readlane_b32 s6, v254, 25
	v_readlane_b32 s38, v254, 33
	s_lshl_b32 s42, s6, 3
	s_lshl_b32 s36, s38, 9
	s_cmp_gt_i32 s38, 0
	s_cselect_b64 s[18:19], -1, 0
	s_cmp_gt_i32 s38, 1
	s_waitcnt vmcnt(3)
	v_lshlrev_b32_e32 v0, 2, v33
	s_cselect_b64 s[20:21], -1, 0
	s_cmp_gt_i32 s38, 2
	v_add_u32_e32 v1, 0xfc, v0
	s_cselect_b64 s[22:23], -1, 0
	s_cmp_gt_i32 s38, 3
	s_waitcnt vmcnt(1)
	v_and_b32_e32 v18, 0xfc, v1
	v_add_u32_e32 v1, 0xf8, v0
	s_cselect_b64 s[24:25], -1, 0
	s_cmp_gt_i32 s38, 4
	v_and_b32_e32 v19, 0xfc, v1
	v_add_u32_e32 v1, 0xf0, v0
	s_cselect_b64 s[26:27], -1, 0
	s_cmp_gt_i32 s38, 5
	v_and_b32_e32 v20, 0xfc, v1
	v_add_u32_e32 v1, 0xe0, v0
	s_cselect_b64 s[28:29], -1, 0
	s_cmp_gt_i32 s38, 6
	v_and_b32_e32 v21, 0xfc, v1
	v_add_u32_e32 v1, 0xc0, v0
	s_cselect_b64 s[30:31], -1, 0
	s_cmp_gt_i32 s38, 7
	v_and_b32_e32 v22, 0xfc, v1
	v_bfrev_b32_e32 v1, 0.5
	s_movk_i32 s16, 0x80
	s_cselect_b64 s[34:35], -1, 0
	s_ashr_i32 s37, s36, 31
	s_lshl_b32 s38, s38, 2
	s_ashr_i32 s97, s96, 31
	v_bitop3_b32 v23, v0, s16, v1 bitop3:0x6c
	v_or_b32_e32 v0, s36, v34
	s_add_i32 s43, s38, 0
	s_and_b32 s38, s96, 7
	s_lshl_b32 s38, s38, 3
	s_lshr_b32 s39, s96, 3
	s_or_b32 s38, s38, s39
	s_lshl_b32 s38, s38, 14
	s_mov_b32 s39, 0
	s_lshl_b64 s[36:37], s[36:37], 2
	s_add_u32 s36, s38, s36
	s_addc_u32 s37, s39, s37
	s_add_u32 s36, s90, s36
	v_mov_b32_e32 v33, v165
	s_addc_u32 s37, s91, s37
	v_readlane_b32 s7, v254, 26
	s_waitcnt lgkmcnt(0)
	v_or_b32_e32 v2, 64, v0
	v_or_b32_e32 v4, 0x80, v0
	v_or_b32_e32 v6, 0xc0, v0
	v_or_b32_e32 v8, 0x100, v0
	v_or_b32_e32 v10, 0x140, v0
	s_waitcnt vmcnt(0)
	v_or_b32_e32 v12, 0x180, v0
	v_or_b32_e32 v14, 0x1c0, v0
	v_lshl_add_u64 v[16:17], s[36:37], 0, v[32:33]
	s_mov_b64 s[36:37], 0x100400
	s_ashr_i32 s83, s82, 31
	v_cmp_eq_u32_e64 s[6:7], 0, v34
	v_cmp_gt_u32_e64 s[8:9], 2, v34
	v_cmp_gt_u32_e64 s[10:11], 4, v34
	v_cmp_gt_u32_e64 s[12:13], 8, v34
	v_cmp_gt_u32_e64 s[14:15], 16, v34
	v_cmp_gt_u32_e64 s[16:17], 32, v34
	v_ashrrev_i32_e32 v1, 31, v0
	v_ashrrev_i32_e32 v3, 31, v2
	v_ashrrev_i32_e32 v5, 31, v4
	v_ashrrev_i32_e32 v7, 31, v6
	v_ashrrev_i32_e32 v9, 31, v8
	v_ashrrev_i32_e32 v11, 31, v10
	v_ashrrev_i32_e32 v13, 31, v12
	v_ashrrev_i32_e32 v15, 31, v14
	v_lshl_add_u64 v[16:17], v[16:17], 0, s[36:37]
	s_lshl_b64 s[36:37], s[82:83], 14
	s_and_b32 s44, s96, 7
	s_lshl_b32 s44, s44, 3
	s_lshr_b32 s45, s96, 3
	s_or_b32 s44, s44, s45
	s_branch .LBB0_512

; #define LAS __attribute__((address_space(3)))
; __device__ __forceinline__ unsigned xb_ld(unsigned* p)              { return __hip_atomic_load(p, __ATOMIC_RELAXED, __HIP_MEMORY_SCOPE_AGENT); }
; __device__ __forceinline__ unsigned xb_xcc_id() { return (unsigned)__builtin_amdgcn_s_getreg((3 << 11) | 20) & 0xFu; }
; __global__ void __launch_bounds__(NTHREADS) mega_kernel(Params p_) {
;     ...
;         if (coop && ph + 1 < ph_hi) {
;             if (ph == 0) {
;                 cg::this_grid().sync();
;                 volatile LAS unsigned* st_ = (volatile LAS unsigned*)(F.lds + 131072 + 64);
;                 if (threadIdx.x == 0) {
;                     unsigned* bar_ = (unsigned*)F.ws; bool ok_ = (gridDim.x % 8u) == 0u;
;                     for (unsigned j = 0; j < 16; ++j) { const unsigned c_ = xb_ld(&bar_[XB_XCNT(j)]); ok_ = ok_ && (c_ == (j < 8u ? gridDim.x / 8u : 0u)); }
;                     const unsigned x_ = xb_xcc_id();
;                     st_[3] = (ok_ && x_ < 8u && st_[2] < gridDim.x / 8u) ? (st_[2] * 8u + x_) : blockIdx.x;
;                 }
;                 __syncthreads();
;             }
;             else { XcdBarrier xb_; xb_.bar = (unsigned*)F.ws; xb_.x = xb_xcc_id(); xb_.st = (volatile LAS unsigned*)(F.lds + 131072 + 64); xcd_barrier(xb_); if (SYNC2) xcd_barrier(xb_); }
.LBB0_790:
	s_andn2_saveexec_b64 s[8:9], s[8:9]
	s_cbranch_execz .LBB0_1139
	v_readlane_b32 s8, v255, 62
	v_readlane_b32 s9, v254, 24
	s_cmp_eq_u32 s8, 0
	s_cbranch_scc1 .Lxb_global
	s_cmpk_lg_i32 s82, 0x100
	s_cbranch_scc1 .Lxb_global
	s_lshr_b32 s8, 0x6ce, s9
	s_bitcmp1_b32 s8, 0
	s_cbranch_scc1 .Lxb_local
